# speedup vs baseline: 1.0026x; 1.0026x over previous
; __device__ __forceinline__ int tidx() { int t = threadIdx.x; asm volatile("" : "+v"(t)); return t; }
; template <int NT, bool LOWREG = false>
; __device__ __forceinline__ void gemm_mainloop(const bh* __restrict__ A, long lda, const bh* __restrict__ B, long ldb, int K,
;                                               char* lds, f32x4 (&acc)[4][NT]) {
;     ...
;   const int tid = tidx(), lane = tid & 63, wid = tid >> 6, wr = wid >> 1, wc = wid & 1, fr = lane & 15, fq = lane >> 4;
;   const int srow = tid >> 3, scol = (tid & 7) * 8;
;   const bh* Ap = A + (long)srow * lda + scol;
;   const bh* Bp = B + (long)srow * ldb + scol;
;   bf16x8 ra[4], rb[NB];
;   const int nk = K >> 6;
; #pragma unroll
;   for (int i = 0; i < 4; ++i) ra[i] = *reinterpret_cast<const bf16x8*>(Ap + (long)(64 * i) * lda);
; #pragma unroll
;   for (int i = 0; i < NB; ++i) rb[i] = *reinterpret_cast<const bf16x8*>(Bp + (long)(64 * i) * ldb);
; #pragma unroll
;   for (int i = 0; i < 4; ++i) *reinterpret_cast<bf16x8*>(lds + (srow + 64 * i) * LROW + scol * 2) = ra[i];
; #pragma unroll
;   for (int i = 0; i < NB; ++i) *reinterpret_cast<bf16x8*>(lds + A_BYTES + (srow + 64 * i) * LROW + scol * 2) = rb[i];
;   __syncthreads();
; #pragma unroll 1
;   for (int kt = 0; kt < nk; ++kt) {
;     const bool more = kt + 1 < nk;
;     if (more) {
; #pragma unroll
;       for (int i = 0; i < 4; ++i) ra[i] = *reinterpret_cast<const bf16x8*>(Ap + (long)(64 * i) * lda + (kt + 1) * 64);
; #pragma unroll
;       for (int i = 0; i < NB; ++i) rb[i] = *reinterpret_cast<const bf16x8*>(Bp + (long)(64 * i) * ldb + (kt + 1) * 64);
;     }
;     ...
;   for (int tile = (t_first >= 0 ? t_first : (int)blockIdx.x); tile < tm_n * tn_n; tile += (t_first >= 0 ? t_stride : (int)gridDim.x)) {
;     const int tn = tile / tm_n, tm = tile - tn * tm_n;
;     f32x4 acc[4][NT];
; #pragma unroll
;     for (int m = 0; m < 4; ++m)
; #pragma unroll
;       for (int n = 0; n < NT; ++n) acc[m][n] = f32x4{0.f, 0.f, 0.f, 0.f};
;     gemm_mainloop<NT>(A + (long)tm * 256 * lda, lda, Bt + (long)tn * BN * ldb, ldb, K, lds, acc);
.LBB0_931:
	s_ashr_i32 s3, s2, 31
	s_lshl_b64 s[14:15], s[2:3], 19
	s_lshr_b32 s3, s3, 26
	s_add_i32 s3, s2, s3
	s_and_b32 s4, s3, 0xffffffc0
	s_sub_i32 s10, s2, s4
	s_ashr_i32 s11, s10, 31
	v_mov_b32_e32 v19, v188
	s_ashr_i32 s12, s3, 6
	s_lshl_b64 s[16:17], s[10:11], 19
	s_add_u32 s20, s38, s16
	v_ashrrev_i32_e32 v32, 3, v19
	v_ashrrev_i32_e32 v33, 31, v32
	s_addc_u32 s21, s39, s17
	v_lshlrev_b64 v[34:35], 11, v[32:33]
	v_lshlrev_b32_e32 v2, 4, v19
	v_lshl_add_u64 v[0:1], s[20:21], 0, v[34:35]
	v_and_b32_e32 v176, 0x70, v2
	v_lshl_add_u64 v[0:1], v[0:1], 0, v[176:177]
	s_mov_b32 s3, 0x20000
	v_add_co_u32_e32 v4, vcc, s3, v0
	s_ashr_i32 s13, s12, 31
	s_nop 0
	v_addc_co_u32_e32 v5, vcc, 0, v1, vcc
	s_mov_b32 s3, 0x40000
	s_lshl_b64 s[16:17], s[12:13], 17
	global_load_dwordx4 v[20:23], v[0:1], off
	global_load_dwordx4 v[24:27], v[4:5], off
	v_add_co_u32_e32 v4, vcc, s3, v0
	s_add_u32 s12, s18, s16
	s_nop 0
	v_addc_co_u32_e32 v5, vcc, 0, v1, vcc
	s_mov_b32 s3, 0x60000
	s_addc_u32 s13, s19, s17
	v_add_co_u32_e32 v0, vcc, s3, v0
	v_lshl_add_u64 v[2:3], s[12:13], 0, v[34:35]
	s_nop 0
	v_addc_co_u32_e32 v1, vcc, 0, v1, vcc
	global_load_dwordx4 v[28:31], v[4:5], off
	global_load_dwordx4 v[36:39], v[0:1], off
	v_lshl_add_u64 v[0:1], v[2:3], 0, v[176:177]
	global_load_dwordx4 v[40:43], v[0:1], off
	v_and_b32_e32 v33, 15, v19
	v_and_b32_e32 v58, 48, v19
	v_lshrrev_b32_e32 v19, 1, v19
	s_mov_b32 s5, 0x7ffffc0
	v_mul_lo_u32 v59, v32, s73
	v_and_or_b32 v32, v19, s5, v33
	v_and_or_b32 v19, v19, 32, v33
	v_mul_lo_u32 v60, v32, s73
	v_lshl_add_u64 v[32:33], s[14:15], 0, v[34:35]
	v_lshl_add_u64 v[34:35], s[16:17], 0, v[34:35]
	s_ashr_i32 s5, s4, 31
	v_mul_u32_u24_e32 v61, 0xa0, v19
	v_or_b32_e32 v19, v32, v176
	v_or_b32_e32 v34, v34, v176
	s_lshl_b64 s[14:15], s[4:5], 19
	v_lshl_add_u64 v[52:53], s[0:1], 0, v[34:35]
	v_mov_b32_e32 v34, s15
	v_subrev_co_u32_e32 v32, vcc, s14, v19
	v_mov_b32_e32 v0, 0
	v_add3_u32 v44, 32, v176, v59
	v_add3_u32 v45, 32, v59, v176
	v_subb_co_u32_e32 v33, vcc, v33, v34, vcc
	s_mov_b32 s3, 0
	s_mov_b64 s[12:13], 0
	v_mov_b32_e32 v1, v0
	v_mov_b32_e32 v2, v0
	v_mov_b32_e32 v3, v0
	v_mov_b32_e32 v4, v0
	v_mov_b32_e32 v5, v0
	v_mov_b32_e32 v6, v0
	v_mov_b32_e32 v7, v0
	v_mov_b32_e32 v8, v0
	v_mov_b32_e32 v9, v0
	v_mov_b32_e32 v10, v0
	v_mov_b32_e32 v11, v0
	v_mov_b32_e32 v12, v0
	v_mov_b32_e32 v13, v0
	v_mov_b32_e32 v14, v0
	v_mov_b32_e32 v15, v0
	v_mov_b32_e32 v16, v0
	v_mov_b32_e32 v17, v0
	v_mov_b32_e32 v18, v0
	v_lshl_add_u64 v[54:55], s[28:29], 0, v[32:33]
	v_mov_b32_e32 v19, v0
	v_mov_b32_e32 v32, v0
	v_mov_b32_e32 v33, v0
	v_mov_b32_e32 v34, v0
	v_mov_b32_e32 v35, v0
	v_mov_b32_e32 v46, v0
	v_mov_b32_e32 v47, v0
	s_waitcnt vmcnt(4)
	ds_write_b128 v44, v[20:23]
	s_waitcnt vmcnt(3)
	ds_write_b128 v44, v[24:27] offset:10240
	s_waitcnt vmcnt(2)
	ds_write_b128 v44, v[28:31] offset:20480
	s_waitcnt vmcnt(1)
	ds_write_b128 v44, v[36:39] offset:30720
	s_waitcnt vmcnt(0)
	ds_write_b128 v45, v[40:43] offset:40960
	v_mov_b32_e32 v44, v0
	v_mov_b32_e32 v45, v0
	v_mov_b32_e32 v48, v0
	v_mov_b32_e32 v49, v0
	v_mov_b32_e32 v50, v0
	v_mov_b32_e32 v51, v0
	v_lshl_add_u64 v[28:29], v[54:55], 0, s[12:13]
	v_add_co_u32_e32 v20, vcc, 0x5770000, v28
	v_lshl_add_u64 v[40:41], v[52:53], 0, s[12:13]
	v_addc_co_u32_e32 v21, vcc, 0, v29, vcc
	v_add_co_u32_e32 v24, vcc, 0x5790000, v28
	s_nop 1
	v_addc_co_u32_e32 v25, vcc, 0, v29, vcc
	v_add_co_u32_e32 v30, vcc, 0x57b0000, v28
	global_load_dwordx4 v[20:23], v[20:21], off offset:128
	s_nop 0
	global_load_dwordx4 v[24:27], v[24:25], off offset:128
	v_addc_co_u32_e32 v31, vcc, 0, v29, vcc
	v_add_co_u32_e32 v36, vcc, 0x57d0000, v28
	s_nop 1
	v_addc_co_u32_e32 v37, vcc, 0, v29, vcc
	global_load_dwordx4 v[28:31], v[30:31], off offset:128
	s_nop 0
	global_load_dwordx4 v[36:39], v[36:37], off offset:128
	s_nop 0
	global_load_dwordx4 v[40:43], v[40:41], off
	v_lshl_add_u64 v[96:97], v[54:55], 0, s[12:13]
	v_add_co_u32_e32 v88, vcc, 0x5770000, v96
	v_lshl_add_u64 v[104:105], v[52:53], 0, s[12:13]
	v_addc_co_u32_e32 v89, vcc, 0, v97, vcc
	v_add_co_u32_e32 v92, vcc, 0x5790000, v96
	s_nop 1
	v_addc_co_u32_e32 v93, vcc, 0, v97, vcc
	v_add_co_u32_e32 v98, vcc, 0x57b0000, v96
	global_load_dwordx4 v[88:91], v[88:89], off offset:256
	s_nop 0
	global_load_dwordx4 v[92:95], v[92:93], off offset:256
	v_addc_co_u32_e32 v99, vcc, 0, v97, vcc
	v_add_co_u32_e32 v100, vcc, 0x57d0000, v96
	s_nop 1
	v_addc_co_u32_e32 v101, vcc, 0, v97, vcc
	global_load_dwordx4 v[96:99], v[98:99], off offset:256
	s_nop 0
	global_load_dwordx4 v[100:103], v[100:101], off offset:256
	s_nop 0
	global_load_dwordx4 v[104:107], v[104:105], off offset:128
	s_waitcnt lgkmcnt(0)
	s_barrier
	s_branch .LBB0_933
; template <int NT, bool LOWREG = false>
; __device__ __forceinline__ void gemm_mainloop(const bh* __restrict__ A, long lda, const bh* __restrict__ B, long ldb, int K,
;                                               char* lds, f32x4 (&acc)[4][NT]) {
;     ...
; #pragma unroll 1
;   for (int kt = 0; kt < nk; ++kt) {
;     const bool more = kt + 1 < nk;
;     if (more) {
; #pragma unroll
;       for (int i = 0; i < 4; ++i) ra[i] = *reinterpret_cast<const bf16x8*>(Ap + (long)(64 * i) * lda + (kt + 1) * 64);
; #pragma unroll
;       for (int i = 0; i < NB; ++i) rb[i] = *reinterpret_cast<const bf16x8*>(Bp + (long)(64 * i) * ldb + (kt + 1) * 64);
;     }
;     const char* sb = lds + (kt & 1) * STAGE;
;     const char* a_base = sb + (wr * 64 + fr) * LROW + fq * 16;
;     const char* b_base = sb + A_BYTES + (wc * (16 * NT) + fr) * LROW + fq * 16;
; #pragma unroll
;     for (int ks = 0; ks < 2; ++ks) {
;       if constexpr (LOWREG) {
;         bf16x8 bfr[NT];
; #pragma unroll
;         for (int n = 0; n < NT; ++n) bfr[n] = *reinterpret_cast<const bf16x8*>(b_base + n * 16 * LROW + ks * 64);
; #pragma unroll
;         for (int mp = 0; mp < 2; ++mp) {
;           bf16x8 af[2];
; #pragma unroll
;           for (int m = 0; m < 2; ++m) af[m] = *reinterpret_cast<const bf16x8*>(a_base + (mp * 2 + m) * 16 * LROW + ks * 64);
;           __builtin_amdgcn_s_setprio(1);
; #pragma unroll
;           for (int m = 0; m < 2; ++m)
; #pragma unroll
;             for (int n = 0; n < NT; ++n) acc[mp * 2 + m][n] = mfma16(af[m], bfr[n], acc[mp * 2 + m][n]);
;           __builtin_amdgcn_s_setprio(0);
;         }
;       } else {
;       bf16x8 af[4], bfr[NT];
; #pragma unroll
;       for (int m = 0; m < 4; ++m) af[m] = *reinterpret_cast<const bf16x8*>(a_base + m * 16 * LROW + ks * 64);
; #pragma unroll
;       for (int n = 0; n < NT; ++n) bfr[n] = *reinterpret_cast<const bf16x8*>(b_base + n * 16 * LROW + ks * 64);
;       __builtin_amdgcn_s_setprio(1);
; #pragma unroll
;       for (int m = 0; m < 4; ++m)
; #pragma unroll
;         for (int n = 0; n < NT; ++n) acc[m][n] = mfma16(af[m], bfr[n], acc[m][n]);
;       __builtin_amdgcn_s_setprio(0);
;       }
;     }
;     if (more) {
;       char* wb = lds + ((kt + 1) & 1) * STAGE;
; #pragma unroll
;       for (int i = 0; i < 4; ++i) *reinterpret_cast<bf16x8*>(wb + (srow + 64 * i) * LROW + scol * 2) = ra[i];
; #pragma unroll
.LBB0_932:
	s_add_u32 s12, s12, 0x80
	s_addc_u32 s13, s13, 0
	s_cmpk_ge_i32 s12, 0x700
	s_cbranch_scc1 .Lmy_2a_skipA_932
	v_lshl_add_u64 v[28:29], v[54:55], 0, s[12:13]
	v_add_co_u32_e32 v20, vcc, 0x5770000, v28
	v_lshl_add_u64 v[40:41], v[52:53], 0, s[12:13]
	v_addc_co_u32_e32 v21, vcc, 0, v29, vcc
	v_add_co_u32_e32 v24, vcc, 0x5790000, v28
	s_nop 1
	v_addc_co_u32_e32 v25, vcc, 0, v29, vcc
	v_add_co_u32_e32 v30, vcc, 0x57b0000, v28
	global_load_dwordx4 v[20:23], v[20:21], off offset:256
	s_nop 0
	global_load_dwordx4 v[24:27], v[24:25], off offset:256
	v_addc_co_u32_e32 v31, vcc, 0, v29, vcc
	v_add_co_u32_e32 v36, vcc, 0x57d0000, v28
	s_nop 1
	v_addc_co_u32_e32 v37, vcc, 0, v29, vcc
	global_load_dwordx4 v[28:31], v[30:31], off offset:256
	s_nop 0
	global_load_dwordx4 v[36:39], v[36:37], off offset:256
	s_nop 0
	global_load_dwordx4 v[40:43], v[40:41], off offset:128
.Lmy_2a_skipA_932:
	s_mov_b32 s3, s5
	s_waitcnt lgkmcnt(0)
	s_barrier
	s_add_i32 s5, s3, 1
	s_bitcmp1_b32 s3, 0
	s_cselect_b32 s3, 0xc800, 0
	s_add_i32 s3, s3, 32
	v_add3_u32 v86, s3, v60, v58
	v_add3_u32 v87, s3, v61, v58
	ds_read_b128 v[62:65], v86
	ds_read_b128 v[66:69], v86 offset:2560
	ds_read_b128 v[70:73], v86 offset:5120
	ds_read_b128 v[74:77], v86 offset:7680
	ds_read_b128 v[78:81], v87 offset:40960
	ds_read_b128 v[82:85], v87 offset:43520
	s_setprio 1
	s_waitcnt lgkmcnt(1)
	v_mfma_f32_16x16x32_bf16 v[48:51], v[62:65], v[78:81], v[48:51]
	s_waitcnt lgkmcnt(0)
	v_mfma_f32_16x16x32_bf16 v[44:47], v[62:65], v[82:85], v[44:47]
	v_mfma_f32_16x16x32_bf16 v[32:35], v[66:69], v[78:81], v[32:35]
	v_mfma_f32_16x16x32_bf16 v[16:19], v[66:69], v[82:85], v[16:19]
	v_mfma_f32_16x16x32_bf16 v[12:15], v[70:73], v[78:81], v[12:15]
	v_mfma_f32_16x16x32_bf16 v[8:11], v[70:73], v[82:85], v[8:11]
	v_mfma_f32_16x16x32_bf16 v[4:7], v[74:77], v[78:81], v[4:7]
	v_mfma_f32_16x16x32_bf16 v[0:3], v[74:77], v[82:85], v[0:3]
	s_setprio 0
	ds_read_b128 v[62:65], v86 offset:64
	ds_read_b128 v[66:69], v86 offset:2624
	ds_read_b128 v[70:73], v86 offset:5184
	ds_read_b128 v[74:77], v86 offset:7744
	ds_read_b128 v[78:81], v87 offset:41024
	ds_read_b128 v[82:85], v87 offset:43584
	s_cmpk_eq_i32 s12, 0x780
	s_cbranch_scc1 .Lmy_2a_lastB_932
	s_bitcmp1_b32 s5, 0
	s_cselect_b32 s3, 0xc800, 0
	s_add_i32 s3, s3, 32
	s_setprio 1
	s_waitcnt lgkmcnt(1)
	v_mfma_f32_16x16x32_bf16 v[48:51], v[62:65], v[78:81], v[48:51]
	s_waitcnt lgkmcnt(0)
	v_mfma_f32_16x16x32_bf16 v[44:47], v[62:65], v[82:85], v[44:47]
	v_mfma_f32_16x16x32_bf16 v[32:35], v[66:69], v[78:81], v[32:35]
	v_add3_u32 v62, s3, v176, v59
	s_waitcnt vmcnt(9)
	ds_write_b128 v62, v[88:91]
	v_mfma_f32_16x16x32_bf16 v[16:19], v[66:69], v[82:85], v[16:19]
	s_waitcnt vmcnt(8)
	ds_write_b128 v62, v[92:95] offset:10240
	v_mfma_f32_16x16x32_bf16 v[12:15], v[70:73], v[78:81], v[12:15]
	s_waitcnt vmcnt(7)
	ds_write_b128 v62, v[96:99] offset:20480
	v_mfma_f32_16x16x32_bf16 v[8:11], v[70:73], v[82:85], v[8:11]
	s_waitcnt vmcnt(6)
	ds_write_b128 v62, v[100:103] offset:30720
	v_mfma_f32_16x16x32_bf16 v[4:7], v[74:77], v[78:81], v[4:7]
	v_add3_u32 v62, s3, v59, v176
	s_waitcnt vmcnt(5)
	ds_write_b128 v62, v[104:107] offset:40960
	v_mfma_f32_16x16x32_bf16 v[0:3], v[74:77], v[82:85], v[0:3]
	s_setprio 0
	s_branch .Lmy_2a_latchB_932

; template <int NT, bool LOWREG = false>
; __device__ __forceinline__ void gemm_mainloop(const bh* __restrict__ A, long lda, const bh* __restrict__ B, long ldb, int K,
;                                               char* lds, f32x4 (&acc)[4][NT]) {
;     ...
;   for (int kt = 0; kt < nk; ++kt) {
;     const bool more = kt + 1 < nk;
;     if (more) {
; #pragma unroll
;       for (int i = 0; i < 4; ++i) ra[i] = *reinterpret_cast<const bf16x8*>(Ap + (long)(64 * i) * lda + (kt + 1) * 64);
; #pragma unroll
;       for (int i = 0; i < NB; ++i) rb[i] = *reinterpret_cast<const bf16x8*>(Bp + (long)(64 * i) * ldb + (kt + 1) * 64);
;     }
.Lmy_2a_latchB_932:
	s_add_u32 s12, s12, 0x80
	s_addc_u32 s13, s13, 0
	s_cmpk_ge_i32 s12, 0x700
	s_cbranch_scc1 .Lmy_2a_skipB_932
	v_lshl_add_u64 v[96:97], v[54:55], 0, s[12:13]
	v_add_co_u32_e32 v88, vcc, 0x5770000, v96
	v_lshl_add_u64 v[104:105], v[52:53], 0, s[12:13]
	v_addc_co_u32_e32 v89, vcc, 0, v97, vcc
	v_add_co_u32_e32 v92, vcc, 0x5790000, v96
	s_nop 1
	v_addc_co_u32_e32 v93, vcc, 0, v97, vcc
	v_add_co_u32_e32 v98, vcc, 0x57b0000, v96
	global_load_dwordx4 v[88:91], v[88:89], off offset:256
	s_nop 0
	global_load_dwordx4 v[92:95], v[92:93], off offset:256
	v_addc_co_u32_e32 v99, vcc, 0, v97, vcc
	v_add_co_u32_e32 v100, vcc, 0x57d0000, v96
	s_nop 1
	v_addc_co_u32_e32 v101, vcc, 0, v97, vcc
	global_load_dwordx4 v[96:99], v[98:99], off offset:256
	s_nop 0
	global_load_dwordx4 v[100:103], v[100:101], off offset:256
	s_nop 0
	global_load_dwordx4 v[104:107], v[104:105], off offset:128

; __device__ __forceinline__ f32x4 mfma16(bf16x8 a, bf16x8 b, f32x4 c) { return __builtin_amdgcn_mfma_f32_16x16x32_bf16(a, b, c, 0, 0, 0); }
; template <int NT, bool LOWREG = false>
; __device__ __forceinline__ void gemm_mainloop(const bh* __restrict__ A, long lda, const bh* __restrict__ B, long ldb, int K,
;                                               char* lds, f32x4 (&acc)[4][NT]) {
;     ...
;     const char* sb = lds + (kt & 1) * STAGE;
;     const char* a_base = sb + (wr * 64 + fr) * LROW + fq * 16;
;     const char* b_base = sb + A_BYTES + (wc * (16 * NT) + fr) * LROW + fq * 16;
; #pragma unroll
;     for (int ks = 0; ks < 2; ++ks) {
;       if constexpr (LOWREG) {
;         bf16x8 bfr[NT];
; #pragma unroll
;         for (int n = 0; n < NT; ++n) bfr[n] = *reinterpret_cast<const bf16x8*>(b_base + n * 16 * LROW + ks * 64);
; #pragma unroll
;         for (int mp = 0; mp < 2; ++mp) {
;           bf16x8 af[2];
; #pragma unroll
;           for (int m = 0; m < 2; ++m) af[m] = *reinterpret_cast<const bf16x8*>(a_base + (mp * 2 + m) * 16 * LROW + ks * 64);
;           __builtin_amdgcn_s_setprio(1);
; #pragma unroll
;           for (int m = 0; m < 2; ++m)
; #pragma unroll
;             for (int n = 0; n < NT; ++n) acc[mp * 2 + m][n] = mfma16(af[m], bfr[n], acc[mp * 2 + m][n]);
;           __builtin_amdgcn_s_setprio(0);
;         }
;       } else {
;       bf16x8 af[4], bfr[NT];
; #pragma unroll
;       for (int m = 0; m < 4; ++m) af[m] = *reinterpret_cast<const bf16x8*>(a_base + m * 16 * LROW + ks * 64);
; #pragma unroll
;       for (int n = 0; n < NT; ++n) bfr[n] = *reinterpret_cast<const bf16x8*>(b_base + n * 16 * LROW + ks * 64);
;       __builtin_amdgcn_s_setprio(1);
; #pragma unroll
;       for (int m = 0; m < 4; ++m)
; #pragma unroll
;         for (int n = 0; n < NT; ++n) acc[m][n] = mfma16(af[m], bfr[n], acc[m][n]);
;       __builtin_amdgcn_s_setprio(0);
;       }
;     }
;     if (more) {
;       char* wb = lds + ((kt + 1) & 1) * STAGE;
; #pragma unroll
;       for (int i = 0; i < 4; ++i) *reinterpret_cast<bf16x8*>(wb + (srow + 64 * i) * LROW + scol * 2) = ra[i];
; #pragma unroll
;       for (int i = 0; i < NB; ++i) *reinterpret_cast<bf16x8*>(wb + A_BYTES + (srow + 64 * i) * LROW + scol * 2) = rb[i];
;     }
;     __syncthreads();
.LBB0_933:
	s_add_i32 s5, s3, 1
	s_bitcmp1_b32 s3, 0
	s_cselect_b32 s3, 0xc800, 0
	s_add_i32 s3, s3, 32
	v_add3_u32 v86, s3, v60, v58
	v_add3_u32 v87, s3, v61, v58
	ds_read_b128 v[62:65], v86
	ds_read_b128 v[66:69], v86 offset:2560
	ds_read_b128 v[70:73], v86 offset:5120
	ds_read_b128 v[74:77], v86 offset:7680
	ds_read_b128 v[78:81], v87 offset:40960
	ds_read_b128 v[82:85], v87 offset:43520
	s_setprio 1
	s_waitcnt lgkmcnt(1)
	v_mfma_f32_16x16x32_bf16 v[48:51], v[62:65], v[78:81], v[48:51]
	s_waitcnt lgkmcnt(0)
	v_mfma_f32_16x16x32_bf16 v[44:47], v[62:65], v[82:85], v[44:47]
	v_mfma_f32_16x16x32_bf16 v[32:35], v[66:69], v[78:81], v[32:35]
	v_mfma_f32_16x16x32_bf16 v[16:19], v[66:69], v[82:85], v[16:19]
	v_mfma_f32_16x16x32_bf16 v[12:15], v[70:73], v[78:81], v[12:15]
	v_mfma_f32_16x16x32_bf16 v[8:11], v[70:73], v[82:85], v[8:11]
	v_mfma_f32_16x16x32_bf16 v[4:7], v[74:77], v[78:81], v[4:7]
	v_mfma_f32_16x16x32_bf16 v[0:3], v[74:77], v[82:85], v[0:3]
	s_setprio 0
	ds_read_b128 v[62:65], v86 offset:64
	ds_read_b128 v[66:69], v86 offset:2624
	ds_read_b128 v[70:73], v86 offset:5184
	ds_read_b128 v[74:77], v86 offset:7744
	ds_read_b128 v[78:81], v87 offset:41024
	ds_read_b128 v[82:85], v87 offset:43584
	s_cmpk_eq_i32 s12, 0x700
	s_cbranch_scc1 .Lmy_2a_tailA_932
	s_bitcmp1_b32 s5, 0
	s_cselect_b32 s3, 0xc800, 0
	s_add_i32 s3, s3, 32
	s_setprio 1
	s_waitcnt lgkmcnt(1)
	v_mfma_f32_16x16x32_bf16 v[48:51], v[62:65], v[78:81], v[48:51]
	s_waitcnt lgkmcnt(0)
	v_mfma_f32_16x16x32_bf16 v[44:47], v[62:65], v[82:85], v[44:47]
	v_mfma_f32_16x16x32_bf16 v[32:35], v[66:69], v[78:81], v[32:35]
	v_add3_u32 v62, s3, v176, v59
	s_waitcnt vmcnt(9)
	ds_write_b128 v62, v[20:23]
	v_mfma_f32_16x16x32_bf16 v[16:19], v[66:69], v[82:85], v[16:19]
	s_waitcnt vmcnt(8)
	ds_write_b128 v62, v[24:27] offset:10240
	v_mfma_f32_16x16x32_bf16 v[12:15], v[70:73], v[78:81], v[12:15]
	s_waitcnt vmcnt(7)
	ds_write_b128 v62, v[28:31] offset:20480
	v_mfma_f32_16x16x32_bf16 v[8:11], v[70:73], v[82:85], v[8:11]
	s_waitcnt vmcnt(6)
	ds_write_b128 v62, v[36:39] offset:30720
	v_mfma_f32_16x16x32_bf16 v[4:7], v[74:77], v[78:81], v[4:7]
	v_add3_u32 v62, s3, v59, v176
	s_waitcnt vmcnt(5)
	ds_write_b128 v62, v[40:43] offset:40960
	v_mfma_f32_16x16x32_bf16 v[0:3], v[74:77], v[82:85], v[0:3]
	s_setprio 0
	s_branch .LBB0_932
.Lmy_2a_tailA_932:
	s_bitcmp1_b32 s5, 0
	s_cselect_b32 s3, 0xc800, 0
	s_add_i32 s3, s3, 32
	s_setprio 1
	s_waitcnt lgkmcnt(1)
	v_mfma_f32_16x16x32_bf16 v[48:51], v[62:65], v[78:81], v[48:51]
	s_waitcnt lgkmcnt(0)
	v_mfma_f32_16x16x32_bf16 v[44:47], v[62:65], v[82:85], v[44:47]
	v_mfma_f32_16x16x32_bf16 v[32:35], v[66:69], v[78:81], v[32:35]
	v_add3_u32 v62, s3, v176, v59
	s_waitcnt vmcnt(4)
	ds_write_b128 v62, v[20:23]
	v_mfma_f32_16x16x32_bf16 v[16:19], v[66:69], v[82:85], v[16:19]
	s_waitcnt vmcnt(3)
	ds_write_b128 v62, v[24:27] offset:10240
	v_mfma_f32_16x16x32_bf16 v[12:15], v[70:73], v[78:81], v[12:15]
	s_waitcnt vmcnt(2)
	ds_write_b128 v62, v[28:31] offset:20480
	v_mfma_f32_16x16x32_bf16 v[8:11], v[70:73], v[82:85], v[8:11]
	s_waitcnt vmcnt(1)
	ds_write_b128 v62, v[36:39] offset:30720
	v_mfma_f32_16x16x32_bf16 v[4:7], v[74:77], v[78:81], v[4:7]
	v_add3_u32 v62, s3, v59, v176
	s_waitcnt vmcnt(0)
	ds_write_b128 v62, v[40:43] offset:40960
	v_mfma_f32_16x16x32_bf16 v[0:3], v[74:77], v[82:85], v[0:3]
	s_setprio 0
	s_branch .LBB0_932
